# v15 + write-through (sc1) stores in the conv and pool_stats phases so the barrier leader's L2 write-back has nothing left to flush
# baseline (speedup 1.0000x reference)
.LBB0_560:
	v_ashrrev_i32_e32 v40, 7, v38
	v_max_i32_e32 v1, 1, v40
	v_add_u32_e32 v96, -1, v1
	v_max_i32_e32 v1, 2, v40
	v_ashrrev_i32_e32 v41, 31, v40
	v_add_u32_e32 v48, -2, v1
	v_lshlrev_b64 v[56:57], 11, v[40:41]
	v_lshlrev_b64 v[44:45], 11, v[96:97]
	v_mov_b32_e32 v49, v97
	v_cmp_lt_i32_e32 vcc, 0, v40
	v_cmp_lt_i32_e64 s[2:3], 1, v40
	v_lshl_add_u64 v[40:41], v[24:25], 0, v[56:57]
	v_lshl_add_u64 v[44:45], v[24:25], 0, v[44:45]
	v_lshlrev_b64 v[48:49], 11, v[48:49]
	global_load_dwordx4 v[40:43], v[40:41], off
	v_lshl_add_u64 v[48:49], v[24:25], 0, v[48:49]
	global_load_dwordx4 v[44:47], v[44:45], off
	v_lshl_add_u64 v[52:53], v[26:27], 0, v[56:57]
	global_load_dwordx4 v[48:51], v[48:49], off
	v_cndmask_b32_e64 v31, 0, 1.0, vcc
	global_load_dwordx4 v[52:55], v[52:53], off
	v_cndmask_b32_e64 v39, 0, 1.0, s[2:3]
	s_waitcnt vmcnt(7)
	v_mul_f32_e32 v1, v8, v31
	s_waitcnt vmcnt(5)
	v_mul_f32_e32 v3, v16, v39
	v_mul_f32_e32 v37, v9, v31
	v_mul_f32_e32 v35, v11, v31
	v_add_u32_e32 v38, s8, v38
	s_mov_b32 s2, 0x1fffff
	v_cmp_lt_i32_e32 vcc, s2, v38
	s_or_b64 s[6:7], vcc, s[6:7]
	s_waitcnt vmcnt(3)
	v_lshlrev_b32_e32 v58, 16, v40
	s_waitcnt vmcnt(2)
	v_lshlrev_b32_e32 v59, 16, v44
	v_pk_mul_f32 v[58:59], v[0:1], v[58:59]
	s_waitcnt vmcnt(1)
	v_lshlrev_b32_e32 v5, 16, v48
	v_fma_f32 v1, v3, v5, v59
	v_add_f32_e32 v1, v58, v1
	v_and_b32_e32 v59, 0xffff0000, v44
	v_and_b32_e32 v58, 0xffff0000, v40
	v_mul_f32_e32 v3, v17, v39
	v_and_b32_e32 v5, 0xffff0000, v48
	v_pk_mul_f32 v[58:59], v[36:37], v[58:59]
	v_lshlrev_b32_e32 v7, 16, v49
	v_fma_f32 v3, v3, v5, v59
	v_add_f32_e32 v37, v58, v3
	v_mul_f32_e32 v3, v10, v31
	v_lshlrev_b32_e32 v58, 16, v41
	v_lshlrev_b32_e32 v59, 16, v45
	v_mul_f32_e32 v5, v18, v39
	v_pk_mul_f32 v[58:59], v[2:3], v[58:59]
	v_and_b32_e32 v45, 0xffff0000, v45
	v_and_b32_e32 v44, 0xffff0000, v41
	v_fma_f32 v3, v5, v7, v59
	v_mul_f32_e32 v5, v19, v39
	v_and_b32_e32 v7, 0xffff0000, v49
	v_pk_mul_f32 v[40:41], v[34:35], v[44:45]
	v_lshlrev_b32_e32 v33, 16, v50
	v_fma_f32 v5, v5, v7, v41
	v_add_f32_e32 v35, v40, v5
	v_mul_f32_e32 v5, v12, v31
	v_lshlrev_b32_e32 v40, 16, v42
	v_lshlrev_b32_e32 v41, 16, v46
	v_mul_f32_e32 v7, v20, v39
	v_pk_mul_f32 v[40:41], v[4:5], v[40:41]
	v_and_b32_e32 v44, 0xffff0000, v50
	v_fma_f32 v5, v7, v33, v41
	v_add_f32_e32 v5, v40, v5
	v_mul_f32_e32 v33, v13, v31
	v_and_b32_e32 v41, 0xffff0000, v46
	v_and_b32_e32 v40, 0xffff0000, v42
	v_mul_f32_e32 v7, v21, v39
	v_pk_mul_f32 v[40:41], v[32:33], v[40:41]
	v_mul_f32_e32 v42, v22, v39
	v_fma_f32 v7, v7, v44, v41
	v_add_f32_e32 v33, v40, v7
	v_mul_f32_e32 v7, v14, v31
	v_lshlrev_b32_e32 v40, 16, v43
	v_lshlrev_b32_e32 v41, 16, v47
	v_lshlrev_b32_e32 v44, 16, v51
	v_pk_mul_f32 v[40:41], v[6:7], v[40:41]
	v_mul_f32_e32 v31, v15, v31
	v_fma_f32 v7, v42, v44, v41
	v_add_f32_e32 v7, v40, v7
	v_and_b32_e32 v41, 0xffff0000, v47
	v_and_b32_e32 v40, 0xffff0000, v43
	v_mul_f32_e32 v39, v23, v39
	v_and_b32_e32 v42, 0xffff0000, v51
	v_pk_mul_f32 v[40:41], v[30:31], v[40:41]
	v_add_f32_e32 v3, v58, v3
	v_fma_f32 v31, v39, v42, v41
	s_waitcnt vmcnt(0)
	v_lshlrev_b32_e32 v39, 16, v52
	v_mul_f32_e32 v1, v1, v39
	v_and_b32_e32 v39, 0xffff0000, v52
	v_add_f32_e32 v31, v40, v31
	v_mul_f32_e32 v37, v37, v39
	v_cvt_pk_bf16_f32 v40, v1, v37
	v_lshlrev_b32_e32 v1, 16, v53
	v_mul_f32_e32 v1, v3, v1
	v_and_b32_e32 v3, 0xffff0000, v53
	v_mul_f32_e32 v3, v35, v3
	v_cvt_pk_bf16_f32 v41, v1, v3
	v_lshlrev_b32_e32 v1, 16, v54
	v_and_b32_e32 v3, 0xffff0000, v54
	v_mul_f32_e32 v1, v5, v1
	v_mul_f32_e32 v3, v33, v3
	v_cvt_pk_bf16_f32 v42, v1, v3
	v_lshlrev_b32_e32 v1, 16, v55
	v_and_b32_e32 v3, 0xffff0000, v55
	v_lshl_add_u64 v[44:45], v[28:29], 0, v[56:57]
	v_mul_f32_e32 v1, v7, v1
	v_mul_f32_e32 v3, v31, v3
	v_cvt_pk_bf16_f32 v43, v1, v3
	global_store_dwordx4 v[44:45], v[40:43], off sc1
	s_andn2_b64 exec, exec, s[6:7]
	s_cbranch_execnz .LBB0_560

.LPS_IC0:
	v_lshlrev_b32_e32 v88, 16, v128
	v_and_b32_e32 v89, 0xffff0000, v128
	v_lshlrev_b32_e32 v90, 16, v129
	v_and_b32_e32 v91, 0xffff0000, v129
	v_lshlrev_b32_e32 v92, 16, v130
	v_and_b32_e32 v93, 0xffff0000, v130
	v_lshlrev_b32_e32 v94, 16, v131
	v_and_b32_e32 v95, 0xffff0000, v131
	v_fma_f32 v0, v80, v0, -v88
	v_fma_f32 v1, v80, v1, -v89
	v_fma_f32 v2, v80, v2, -v90
	v_fma_f32 v3, v80, v3, -v91
	v_fma_f32 v4, v80, v4, -v92
	v_fma_f32 v5, v80, v5, -v93
	v_fma_f32 v6, v80, v6, -v94
	v_fma_f32 v7, v80, v7, -v95
	v_cvt_pk_bf16_f32 v0, v0, v1
	v_cvt_pk_bf16_f32 v1, v2, v3
	v_cvt_pk_bf16_f32 v2, v4, v5
	v_cvt_pk_bf16_f32 v3, v6, v7
	global_store_dwordx4 v192, v[0:3], s[14:15] sc1
	s_cmp_lt_u32 s12, 16
	s_cbranch_scc0 .LPS_IC1
	s_add_i32 s13, s12, 2
	v_min_i32_e32 v81, s13, v195
	v_cvt_f32_i32_e32 v81, v81
	v_div_scale_f32 v82, s[26:27], v81, v81, 1.0
	v_rcp_f32_e32 v85, v82
	s_nop 0
	v_fma_f32 v83, -v82, v85, 1.0
	v_fmac_f32_e32 v85, v83, v85
	v_div_scale_f32 v83, vcc, 1.0, v81, 1.0
	v_mul_f32_e32 v86, v83, v85
	v_fma_f32 v84, -v82, v86, v83
	v_fmac_f32_e32 v86, v84, v85
	v_fma_f32 v83, -v82, v86, v83
	v_div_fmas_f32 v83, v83, v85, v86
	v_div_fixup_f32 v80, v83, v81, 1.0

.LPS_IC1:
	v_lshlrev_b32_e32 v88, 16, v124
	v_and_b32_e32 v89, 0xffff0000, v124
	v_lshlrev_b32_e32 v90, 16, v125
	v_and_b32_e32 v91, 0xffff0000, v125
	v_lshlrev_b32_e32 v92, 16, v126
	v_and_b32_e32 v93, 0xffff0000, v126
	v_lshlrev_b32_e32 v94, 16, v127
	v_and_b32_e32 v95, 0xffff0000, v127
	v_fma_f32 v8, v80, v8, -v88
	v_fma_f32 v9, v80, v9, -v89
	v_fma_f32 v10, v80, v10, -v90
	v_fma_f32 v11, v80, v11, -v91
	v_fma_f32 v12, v80, v12, -v92
	v_fma_f32 v13, v80, v13, -v93
	v_fma_f32 v14, v80, v14, -v94
	v_fma_f32 v15, v80, v15, -v95
	v_cvt_pk_bf16_f32 v8, v8, v9
	v_cvt_pk_bf16_f32 v9, v10, v11
	v_cvt_pk_bf16_f32 v10, v12, v13
	v_cvt_pk_bf16_f32 v11, v14, v15
	s_add_u32 s14, s14, 0x800
	s_addc_u32 s15, s15, 0
	global_store_dwordx4 v192, v[8:11], s[14:15] sc1
	s_cmp_lt_u32 s12, 16
	s_cbranch_scc0 .LPS_IC2
	s_add_i32 s13, s12, 3
	v_min_i32_e32 v81, s13, v195
	v_cvt_f32_i32_e32 v81, v81
	v_div_scale_f32 v82, s[26:27], v81, v81, 1.0
	v_rcp_f32_e32 v85, v82
	s_nop 0
	v_fma_f32 v83, -v82, v85, 1.0
	v_fmac_f32_e32 v85, v83, v85
	v_div_scale_f32 v83, vcc, 1.0, v81, 1.0
	v_mul_f32_e32 v86, v83, v85
	v_fma_f32 v84, -v82, v86, v83
	v_fmac_f32_e32 v86, v84, v85
	v_fma_f32 v83, -v82, v86, v83
	v_div_fmas_f32 v83, v83, v85, v86
	v_div_fixup_f32 v80, v83, v81, 1.0

.LPS_IC2:
	v_lshlrev_b32_e32 v88, 16, v120
	v_and_b32_e32 v89, 0xffff0000, v120
	v_lshlrev_b32_e32 v90, 16, v121
	v_and_b32_e32 v91, 0xffff0000, v121
	v_lshlrev_b32_e32 v92, 16, v122
	v_and_b32_e32 v93, 0xffff0000, v122
	v_lshlrev_b32_e32 v94, 16, v123
	v_and_b32_e32 v95, 0xffff0000, v123
	v_fma_f32 v16, v80, v16, -v88
	v_fma_f32 v17, v80, v17, -v89
	v_fma_f32 v18, v80, v18, -v90
	v_fma_f32 v19, v80, v19, -v91
	v_fma_f32 v20, v80, v20, -v92
	v_fma_f32 v21, v80, v21, -v93
	v_fma_f32 v22, v80, v22, -v94
	v_fma_f32 v23, v80, v23, -v95
	v_cvt_pk_bf16_f32 v16, v16, v17
	v_cvt_pk_bf16_f32 v17, v18, v19
	v_cvt_pk_bf16_f32 v18, v20, v21
	v_cvt_pk_bf16_f32 v19, v22, v23
	s_add_u32 s14, s14, 0x800
	s_addc_u32 s15, s15, 0
	global_store_dwordx4 v192, v[16:19], s[14:15] sc1
	s_cmp_lt_u32 s12, 16
	s_cbranch_scc0 .LPS_IC3
	s_add_i32 s13, s12, 4
	v_min_i32_e32 v81, s13, v195
	v_cvt_f32_i32_e32 v81, v81
	v_div_scale_f32 v82, s[26:27], v81, v81, 1.0
	v_rcp_f32_e32 v85, v82
	s_nop 0
	v_fma_f32 v83, -v82, v85, 1.0
	v_fmac_f32_e32 v85, v83, v85
	v_div_scale_f32 v83, vcc, 1.0, v81, 1.0
	v_mul_f32_e32 v86, v83, v85
	v_fma_f32 v84, -v82, v86, v83
	v_fmac_f32_e32 v86, v84, v85
	v_fma_f32 v83, -v82, v86, v83
	v_div_fmas_f32 v83, v83, v85, v86
	v_div_fixup_f32 v80, v83, v81, 1.0

.LPS_IC3:
	v_lshlrev_b32_e32 v88, 16, v116
	v_and_b32_e32 v89, 0xffff0000, v116
	v_lshlrev_b32_e32 v90, 16, v117
	v_and_b32_e32 v91, 0xffff0000, v117
	v_lshlrev_b32_e32 v92, 16, v118
	v_and_b32_e32 v93, 0xffff0000, v118
	v_lshlrev_b32_e32 v94, 16, v119
	v_and_b32_e32 v95, 0xffff0000, v119
	v_fma_f32 v24, v80, v24, -v88
	v_fma_f32 v25, v80, v25, -v89
	v_fma_f32 v26, v80, v26, -v90
	v_fma_f32 v27, v80, v27, -v91
	v_fma_f32 v28, v80, v28, -v92
	v_fma_f32 v29, v80, v29, -v93
	v_fma_f32 v30, v80, v30, -v94
	v_fma_f32 v31, v80, v31, -v95
	v_cvt_pk_bf16_f32 v24, v24, v25
	v_cvt_pk_bf16_f32 v25, v26, v27
	v_cvt_pk_bf16_f32 v26, v28, v29
	v_cvt_pk_bf16_f32 v27, v30, v31
	s_add_u32 s14, s14, 0x800
	s_addc_u32 s15, s15, 0
	global_store_dwordx4 v192, v[24:27], s[14:15] sc1
	s_cmp_lt_u32 s12, 16
	s_cbranch_scc0 .LPS_IC4
	s_add_i32 s13, s12, 5
	v_min_i32_e32 v81, s13, v195
	v_cvt_f32_i32_e32 v81, v81
	v_div_scale_f32 v82, s[26:27], v81, v81, 1.0
	v_rcp_f32_e32 v85, v82
	s_nop 0
	v_fma_f32 v83, -v82, v85, 1.0
	v_fmac_f32_e32 v85, v83, v85
	v_div_scale_f32 v83, vcc, 1.0, v81, 1.0
	v_mul_f32_e32 v86, v83, v85
	v_fma_f32 v84, -v82, v86, v83
	v_fmac_f32_e32 v86, v84, v85
	v_fma_f32 v83, -v82, v86, v83
	v_div_fmas_f32 v83, v83, v85, v86
	v_div_fixup_f32 v80, v83, v81, 1.0

.LPS_IC4:
	v_lshlrev_b32_e32 v88, 16, v112
	v_and_b32_e32 v89, 0xffff0000, v112
	v_lshlrev_b32_e32 v90, 16, v113
	v_and_b32_e32 v91, 0xffff0000, v113
	v_lshlrev_b32_e32 v92, 16, v114
	v_and_b32_e32 v93, 0xffff0000, v114
	v_lshlrev_b32_e32 v94, 16, v115
	v_and_b32_e32 v95, 0xffff0000, v115
	v_fma_f32 v32, v80, v32, -v88
	v_fma_f32 v33, v80, v33, -v89
	v_fma_f32 v34, v80, v34, -v90
	v_fma_f32 v35, v80, v35, -v91
	v_fma_f32 v36, v80, v36, -v92
	v_fma_f32 v37, v80, v37, -v93
	v_fma_f32 v38, v80, v38, -v94
	v_fma_f32 v39, v80, v39, -v95
	v_cvt_pk_bf16_f32 v32, v32, v33
	v_cvt_pk_bf16_f32 v33, v34, v35
	v_cvt_pk_bf16_f32 v34, v36, v37
	v_cvt_pk_bf16_f32 v35, v38, v39
	s_add_u32 s14, s14, 0x800
	s_addc_u32 s15, s15, 0
	global_store_dwordx4 v192, v[32:35], s[14:15] sc1
	s_cmp_lt_u32 s12, 16
	s_cbranch_scc0 .LPS_IC5
	s_add_i32 s13, s12, 6
	v_min_i32_e32 v81, s13, v195
	v_cvt_f32_i32_e32 v81, v81
	v_div_scale_f32 v82, s[26:27], v81, v81, 1.0
	v_rcp_f32_e32 v85, v82
	s_nop 0
	v_fma_f32 v83, -v82, v85, 1.0
	v_fmac_f32_e32 v85, v83, v85
	v_div_scale_f32 v83, vcc, 1.0, v81, 1.0
	v_mul_f32_e32 v86, v83, v85
	v_fma_f32 v84, -v82, v86, v83
	v_fmac_f32_e32 v86, v84, v85
	v_fma_f32 v83, -v82, v86, v83
	v_div_fmas_f32 v83, v83, v85, v86
	v_div_fixup_f32 v80, v83, v81, 1.0

.LPS_IC5:
	v_lshlrev_b32_e32 v88, 16, v108
	v_and_b32_e32 v89, 0xffff0000, v108
	v_lshlrev_b32_e32 v90, 16, v109
	v_and_b32_e32 v91, 0xffff0000, v109
	v_lshlrev_b32_e32 v92, 16, v110
	v_and_b32_e32 v93, 0xffff0000, v110
	v_lshlrev_b32_e32 v94, 16, v111
	v_and_b32_e32 v95, 0xffff0000, v111
	v_fma_f32 v40, v80, v40, -v88
	v_fma_f32 v41, v80, v41, -v89
	v_fma_f32 v42, v80, v42, -v90
	v_fma_f32 v43, v80, v43, -v91
	v_fma_f32 v44, v80, v44, -v92
	v_fma_f32 v45, v80, v45, -v93
	v_fma_f32 v46, v80, v46, -v94
	v_fma_f32 v47, v80, v47, -v95
	v_cvt_pk_bf16_f32 v40, v40, v41
	v_cvt_pk_bf16_f32 v41, v42, v43
	v_cvt_pk_bf16_f32 v42, v44, v45
	v_cvt_pk_bf16_f32 v43, v46, v47
	s_add_u32 s14, s14, 0x800
	s_addc_u32 s15, s15, 0
	global_store_dwordx4 v192, v[40:43], s[14:15] sc1
	s_cmp_lt_u32 s12, 16
	s_cbranch_scc0 .LPS_IC6
	s_add_i32 s13, s12, 7
	v_min_i32_e32 v81, s13, v195
	v_cvt_f32_i32_e32 v81, v81
	v_div_scale_f32 v82, s[26:27], v81, v81, 1.0
	v_rcp_f32_e32 v85, v82
	s_nop 0
	v_fma_f32 v83, -v82, v85, 1.0
	v_fmac_f32_e32 v85, v83, v85
	v_div_scale_f32 v83, vcc, 1.0, v81, 1.0
	v_mul_f32_e32 v86, v83, v85
	v_fma_f32 v84, -v82, v86, v83
	v_fmac_f32_e32 v86, v84, v85
	v_fma_f32 v83, -v82, v86, v83
	v_div_fmas_f32 v83, v83, v85, v86
	v_div_fixup_f32 v80, v83, v81, 1.0

.LPS_IC6:
	v_lshlrev_b32_e32 v88, 16, v104
	v_and_b32_e32 v89, 0xffff0000, v104
	v_lshlrev_b32_e32 v90, 16, v105
	v_and_b32_e32 v91, 0xffff0000, v105
	v_lshlrev_b32_e32 v92, 16, v106
	v_and_b32_e32 v93, 0xffff0000, v106
	v_lshlrev_b32_e32 v94, 16, v107
	v_and_b32_e32 v95, 0xffff0000, v107
	v_fma_f32 v48, v80, v48, -v88
	v_fma_f32 v49, v80, v49, -v89
	v_fma_f32 v50, v80, v50, -v90
	v_fma_f32 v51, v80, v51, -v91
	v_fma_f32 v52, v80, v52, -v92
	v_fma_f32 v53, v80, v53, -v93
	v_fma_f32 v54, v80, v54, -v94
	v_fma_f32 v55, v80, v55, -v95
	v_cvt_pk_bf16_f32 v48, v48, v49
	v_cvt_pk_bf16_f32 v49, v50, v51
	v_cvt_pk_bf16_f32 v50, v52, v53
	v_cvt_pk_bf16_f32 v51, v54, v55
	s_add_u32 s14, s14, 0x800
	s_addc_u32 s15, s15, 0
	global_store_dwordx4 v192, v[48:51], s[14:15] sc1
	s_cmp_lt_u32 s12, 16
	s_cbranch_scc0 .LPS_IC7
	s_add_i32 s13, s12, 8
	v_min_i32_e32 v81, s13, v195
	v_cvt_f32_i32_e32 v81, v81
	v_div_scale_f32 v82, s[26:27], v81, v81, 1.0
	v_rcp_f32_e32 v85, v82
	s_nop 0
	v_fma_f32 v83, -v82, v85, 1.0
	v_fmac_f32_e32 v85, v83, v85
	v_div_scale_f32 v83, vcc, 1.0, v81, 1.0
	v_mul_f32_e32 v86, v83, v85
	v_fma_f32 v84, -v82, v86, v83
	v_fmac_f32_e32 v86, v84, v85
	v_fma_f32 v83, -v82, v86, v83
	v_div_fmas_f32 v83, v83, v85, v86
	v_div_fixup_f32 v80, v83, v81, 1.0

.LPS_IC7:
	v_lshlrev_b32_e32 v88, 16, v100
	v_and_b32_e32 v89, 0xffff0000, v100
	v_lshlrev_b32_e32 v90, 16, v101
	v_and_b32_e32 v91, 0xffff0000, v101
	v_lshlrev_b32_e32 v92, 16, v102
	v_and_b32_e32 v93, 0xffff0000, v102
	v_lshlrev_b32_e32 v94, 16, v103
	v_and_b32_e32 v95, 0xffff0000, v103
	v_fma_f32 v56, v80, v56, -v88
	v_fma_f32 v57, v80, v57, -v89
	v_fma_f32 v58, v80, v58, -v90
	v_fma_f32 v59, v80, v59, -v91
	v_fma_f32 v60, v80, v60, -v92
	v_fma_f32 v61, v80, v61, -v93
	v_fma_f32 v62, v80, v62, -v94
	v_fma_f32 v63, v80, v63, -v95
	v_cvt_pk_bf16_f32 v56, v56, v57
	v_cvt_pk_bf16_f32 v57, v58, v59
	v_cvt_pk_bf16_f32 v58, v60, v61
	v_cvt_pk_bf16_f32 v59, v62, v63
	s_add_u32 s14, s14, 0x800
	s_addc_u32 s15, s15, 0
	global_store_dwordx4 v192, v[56:59], s[14:15] sc1
	s_lshl_b32 s13, s12, 3
	s_add_u32 s14, s10, s13
	s_addc_u32 s15, s11, 0
	s_add_u32 s14, s14, 0x100000
	s_addc_u32 s15, s15, 0
	s_mov_b64 s[16:17], exec
	s_mov_b32 exec_lo, 0
	s_brev_b32 exec_hi, 1
	global_store_dwordx4 v97, v[64:67], s[14:15] sc1
	global_store_dwordx4 v97, v[68:71], s[14:15] offset:16 sc1
	global_store_dwordx4 v97, v[72:75], s[14:15] offset:32 sc1
	global_store_dwordx4 v97, v[76:79], s[14:15] offset:48 sc1
	s_mov_b64 exec, s[16:17]
	s_add_i32 s24, s24, s21
	s_cmpk_lt_i32 s24, 0x800
	s_cbranch_scc1 .LPS_LOOP

